# v9 + prompt-attention K-fragment loads of a key tile issued together
# baseline (speedup 1.0000x reference)
; #define LAS __attribute__((address_space(3)))
; __device__ __forceinline__ f32x16 mma32(bf16x8 a, bf16x8 b, f32x16 c) { return __builtin_amdgcn_mfma_f32_32x32x16_bf16(a, b, c, 0, 0, 0); }
; __device__ __forceinline__ int acc_row(int reg, int hh) { return (reg & 3) + 8 * (reg >> 2) + 4 * hh; }
; __device__ __forceinline__ void attn_prompt_task(const P& p, int l, int s, int qb, int h, LAS unsigned char* ldsw, int lane) {
;     LAS bf16* PT = (LAS bf16*)ldsw;
;     const int r = lane & 31, hh = lane >> 5, g = h >> 2, q0 = 32 * qb;
;     bf16x8 qf[4];
; #pragma unroll
;     for (int ks = 0; ks < 4; ++ks) qf[ks] = *(const bf16x8*)(p.QB16 + (size_t)(s * TP + q0 + r) * 1024 + h * 64 + 16 * ks + 8 * hh);
;     f32x16 st[5];
; #pragma unroll
;     for (int kt = 0; kt < 5; ++kt) {
;         int pk = q0 - 128 + 32 * kt + r; pk = pk < 0 ? 0 : pk;
;         st[kt] = zero16();
; #pragma unroll
;         for (int ks = 0; ks < 4; ++ks) { const bf16x8 kf = *(const bf16x8*)(p.KB16 + (size_t)(s * TP + pk) * 256 + g * 64 + 16 * ks + 8 * hh); st[kt] = mma32(kf, qf[ks], st[kt]); }
;     }
;     const float sink = p.in[9][l * 16 + h];
;     float m = sink;
; #pragma unroll
;     for (int kt = 0; kt < 5; ++kt)
; #pragma unroll
;         for (int reg = 0; reg < 16; ++reg) {
;             const int kk = 32 * kt + acc_row(reg, hh);
;             const bool valid = (kk >= r) && (kk <= r + 128) && (q0 - 128 + kk >= 0);
;             const float v = valid ? st[kt][reg] * 0.125f : -3.0e38f;
;             st[kt][reg] = v; m = fmaxf(m, v);
;         }
.LBB0_1419:
	s_bfe_u32 s8, s6, 0x20002
	s_bfe_u32 s9, s6, 0x70004
	s_mov_b32 s11, s35
	s_lshl_b32 s10, s8, 7
	s_lshl_b32 s7, s9, 5
	v_lshl_add_u64 v[34:35], v[48:49], 0, s[10:11]
	s_add_i32 s10, s7, 0xffffff80
	s_and_b32 s12, s6, 15
	s_ashr_i32 s11, s6, 11
	v_or_b32_e32 v2, s10, v95
	v_or_b32_e32 v3, s10, v46
	s_lshl_b32 s34, s12, 7
	s_lshl_b32 s10, s11, 12
	s_cmp_lt_u32 s9, 4
	s_cselect_b64 s[14:15], -1, 0
	s_add_i32 s13, s7, 0xffffffa0
	v_or_b32_e32 v4, 16, v3
	s_cmp_lt_u32 s9, 3
	v_cndmask_b32_e64 v2, v2, 0, s[14:15]
	v_cndmask_b32_e64 v36, v3, 0, s[14:15]
	v_cndmask_b32_e64 v38, v4, 0, s[14:15]
	v_or_b32_e32 v3, s13, v95
	v_or_b32_e32 v4, s13, v46
	s_cselect_b64 s[14:15], -1, 0
	s_sub_i32 s13, s7, 64
	v_or_b32_e32 v5, 16, v4
	s_cmp_lt_u32 s9, 2
	v_cndmask_b32_e64 v39, v3, 0, s[14:15]
	v_cndmask_b32_e64 v40, v4, 0, s[14:15]
	v_cndmask_b32_e64 v42, v5, 0, s[14:15]
	v_or_b32_e32 v3, s13, v95
	v_or_b32_e32 v4, s13, v46
	s_cselect_b64 s[14:15], -1, 0
	s_sub_i32 s13, s7, 32
	v_or_b32_e32 v5, 16, v4
	s_cmp_eq_u32 s9, 0
	v_cndmask_b32_e64 v41, v3, 0, s[14:15]
	v_cndmask_b32_e64 v44, v4, 0, s[14:15]
	v_cndmask_b32_e64 v104, v5, 0, s[14:15]
	v_or_b32_e32 v3, s13, v95
	s_cselect_b64 s[14:15], -1, 0
	v_cndmask_b32_e64 v120, v3, 0, s[14:15]
	v_or_b32_e32 v3, s10, v95
	v_or_b32_e32 v112, s7, v3
	v_or_b32_e32 v4, s13, v46
	v_ashrrev_i32_e32 v113, 31, v112
	v_or_b32_e32 v5, 16, v4
	s_or_b32 s12, s12, s54
	s_mov_b32 s13, s35
	v_lshlrev_b64 v[102:103], 11, v[112:113]
	v_add_u32_e32 v2, s10, v2
	v_cndmask_b32_e64 v106, v4, 0, s[14:15]
	v_cndmask_b32_e64 v108, v5, 0, s[14:15]
	s_lshl_b64 s[12:13], s[12:13], 2
	v_lshl_add_u64 v[4:5], s[70:71], 0, v[102:103]
	v_ashrrev_i32_e32 v3, 31, v2
	s_add_u32 s12, s78, s12
	v_lshlrev_b32_e32 v162, 1, v46
	v_lshl_add_u64 v[4:5], v[4:5], 0, s[34:35]
	v_lshlrev_b64 v[2:3], 9, v[2:3]
	s_addc_u32 s13, s79, s13
	v_lshl_add_u64 v[4:5], v[4:5], 0, v[162:163]
	v_lshl_add_u64 v[118:119], v[34:35], 0, v[2:3]
	global_load_dword v37, v163, s[12:13]
	global_load_dwordx4 v[30:33], v[4:5], off
	global_load_dwordx4 v[26:29], v[4:5], off offset:32
	global_load_dwordx4 v[22:25], v[4:5], off offset:64
	global_load_dwordx4 v[18:21], v[4:5], off offset:96
	global_load_dwordx4 v[114:117], v[118:119], off offset:32
	global_load_dwordx4 v[238:241], v[118:119], off offset:64
	global_load_dwordx4 v[242:245], v[118:119], off offset:96
	s_lshl_b32 s9, s11, 2
	global_load_dwordx4 v[2:5], v[118:119], off
	s_or_b32 s8, s8, s9
	s_ashr_i32 s9, s8, 31
	s_lshl_b64 s[8:9], s[8:9], 19
	v_or_b32_e32 v110, s8, v100
	s_sub_i32 s8, 0x7f, s7
	v_cmp_lt_i32_e32 vcc, s8, v50
	s_and_b64 vcc, s[22:23], vcc
	v_mov_b32_e32 v111, s9
	v_lshl_add_u64 v[102:103], s[18:19], 0, v[102:103]
	s_add_i32 s6, s6, s16
	s_waitcnt vmcnt(0) lgkmcnt(0)
	v_mfma_f32_32x32x16_bf16 v[2:17], v[2:5], v[30:33], 0
	v_mfma_f32_32x32x16_bf16 v[2:17], v[114:117], v[26:29], v[2:17]
	v_mfma_f32_32x32x16_bf16 v[2:17], v[238:241], v[22:25], v[2:17]
	v_mfma_f32_32x32x16_bf16 v[2:17], v[242:245], v[18:21], v[2:17]
	s_nop 11
	v_mul_f32_e32 v2, 0x3e000000, v2
	v_cndmask_b32_e32 v43, v206, v2, vcc
	v_cmp_le_i32_e32 vcc, s8, v50
	s_and_b64 vcc, s[24:25], vcc
	v_mul_f32_e32 v2, 0x3e000000, v3
	v_cndmask_b32_e32 v45, v206, v2, vcc
	v_cmp_lt_i32_e32 vcc, s8, v97
	s_and_b64 vcc, s[26:27], vcc
	v_mul_f32_e32 v2, 0x3e000000, v4
	v_cndmask_b32_e32 v105, v206, v2, vcc
	v_cmp_lt_i32_e32 vcc, s8, v99
	s_and_b64 vcc, s[36:37], vcc
	v_mul_f32_e32 v2, 0x3e000000, v5
	v_cndmask_b32_e32 v107, v206, v2, vcc
	v_cmp_lt_i32_e32 vcc, s8, v101
	s_and_b64 vcc, s[60:61], vcc
	v_mul_f32_e32 v2, 0x3e000000, v6
	v_cndmask_b32_e32 v109, v206, v2, vcc
	v_cmp_lt_i32_e32 vcc, s8, v146
	s_and_b64 vcc, s[62:63], vcc
	v_mul_f32_e32 v2, 0x3e000000, v7
	v_cndmask_b32_e32 v114, v206, v2, vcc
	v_cmp_lt_i32_e32 vcc, s8, v147
	s_and_b64 vcc, s[64:65], vcc
	v_mul_f32_e32 v2, 0x3e000000, v8
	v_cndmask_b32_e32 v115, v206, v2, vcc
	v_cmp_lt_i32_e32 vcc, s8, v148
	s_and_b64 vcc, s[66:67], vcc
	v_mul_f32_e32 v2, 0x3e000000, v9
	v_cndmask_b32_e32 v116, v206, v2, vcc
	v_cmp_lt_i32_e32 vcc, s8, v149
	s_and_b64 vcc, s[68:69], vcc
	v_mul_f32_e32 v2, 0x3e000000, v10
	v_cndmask_b32_e32 v117, v206, v2, vcc
	v_cmp_lt_i32_e32 vcc, s8, v150
	s_and_b64 vcc, s[72:73], vcc
	v_mul_f32_e32 v2, 0x3e000000, v11
	v_cndmask_b32_e32 v118, v206, v2, vcc
	v_cmp_lt_i32_e32 vcc, s8, v151
	s_and_b64 vcc, s[76:77], vcc
	v_mul_f32_e32 v2, 0x3e000000, v12
	v_cndmask_b32_e32 v119, v206, v2, vcc
	v_cmp_lt_i32_e32 vcc, s8, v152
	s_and_b64 vcc, s[80:81], vcc
	v_mul_f32_e32 v2, 0x3e000000, v13
	v_cndmask_b32_e32 v121, v206, v2, vcc
	v_cmp_lt_i32_e32 vcc, s8, v153
	s_and_b64 vcc, s[82:83], vcc
	v_mul_f32_e32 v2, 0x3e000000, v14
	v_cndmask_b32_e32 v128, v206, v2, vcc
	v_cmp_lt_i32_e32 vcc, s8, v154
	s_and_b64 vcc, s[84:85], vcc
	v_mul_f32_e32 v2, 0x3e000000, v15
	v_cndmask_b32_e32 v129, v206, v2, vcc
	v_cmp_lt_i32_e32 vcc, s8, v155
	s_and_b64 vcc, s[86:87], vcc
	v_mul_f32_e32 v2, 0x3e000000, v16
	v_cndmask_b32_e32 v130, v206, v2, vcc
	v_cmp_lt_i32_e32 vcc, s8, v156
	s_and_b64 vcc, s[88:89], vcc
	v_mul_f32_e32 v2, 0x3e000000, v17
	v_cndmask_b32_e32 v131, v206, v2, vcc
	v_add_u32_e32 v2, s10, v39
	v_ashrrev_i32_e32 v3, 31, v2
	v_lshlrev_b64 v[2:3], 9, v[2:3]
	v_lshl_add_u64 v[126:127], v[34:35], 0, v[2:3]
	global_load_dwordx4 v[2:5], v[126:127], off
	global_load_dwordx4 v[122:125], v[126:127], off offset:32
	global_load_dwordx4 v[238:241], v[126:127], off offset:64
	global_load_dwordx4 v[242:245], v[126:127], off offset:96
	v_cmp_lt_i32_e32 vcc, s8, v47
	s_waitcnt vmcnt(3)
	v_mfma_f32_32x32x16_bf16 v[2:17], v[2:5], v[30:33], 0
	s_cmpk_gt_i32 s6, 0xfff
	s_waitcnt vmcnt(2)
; __device__ __forceinline__ f32x16 mma32(bf16x8 a, bf16x8 b, f32x16 c) { return __builtin_amdgcn_mfma_f32_32x32x16_bf16(a, b, c, 0, 0, 0); }
; __device__ __forceinline__ int acc_row(int reg, int hh) { return (reg & 3) + 8 * (reg >> 2) + 4 * hh; }
; __device__ __forceinline__ void attn_prompt_task(const P& p, int l, int s, int qb, int h, LAS unsigned char* ldsw, int lane) {
;     ...
;     for (int kt = 0; kt < 5; ++kt) {
;         int pk = q0 - 128 + 32 * kt + r; pk = pk < 0 ? 0 : pk;
;         st[kt] = zero16();
; #pragma unroll
;         for (int ks = 0; ks < 4; ++ks) { const bf16x8 kf = *(const bf16x8*)(p.KB16 + (size_t)(s * TP + pk) * 256 + g * 64 + 16 * ks + 8 * hh); st[kt] = mma32(kf, qf[ks], st[kt]); }
;     }
;     const float sink = p.in[9][l * 16 + h];
;     float m = sink;
; #pragma unroll
;     for (int kt = 0; kt < 5; ++kt)
; #pragma unroll
;         for (int reg = 0; reg < 16; ++reg) {
;             const int kk = 32 * kt + acc_row(reg, hh);
;             const bool valid = (kk >= r) && (kk <= r + 128) && (q0 - 128 + kk >= 0);
;             const float v = valid ? st[kt][reg] * 0.125f : -3.0e38f;
;             st[kt][reg] = v; m = fmaxf(m, v);
;         }
	v_mfma_f32_32x32x16_bf16 v[2:17], v[122:125], v[26:29], v[2:17]
	s_waitcnt vmcnt(1)
	v_mfma_f32_32x32x16_bf16 v[2:17], v[238:241], v[22:25], v[2:17]
	s_waitcnt vmcnt(0)
	v_mfma_f32_32x32x16_bf16 v[2:17], v[242:245], v[18:21], v[2:17]
	s_nop 11
	v_pk_mul_f32 v[4:5], v[4:5], s[20:21] op_sel_hi:[1,0]
	s_nop 0
	v_cndmask_b32_e32 v39, v206, v5, vcc
	v_cmp_lt_i32_e32 vcc, s8, v54
	v_pk_mul_f32 v[2:3], v[2:3], s[20:21] op_sel_hi:[1,0]
	s_nop 0
	v_cndmask_b32_e32 v132, v206, v4, vcc
	v_cmp_lt_i32_e32 vcc, s8, v1
	s_nop 1
	v_cndmask_b32_e32 v133, v206, v3, vcc
	v_cmp_lt_i32_e32 vcc, s8, v52
	s_nop 1
	v_cndmask_b32_e32 v134, v206, v2, vcc
	v_pk_mul_f32 v[2:3], v[8:9], s[20:21] op_sel_hi:[1,0]
	v_cmp_lt_i32_e32 vcc, s8, v53
	s_nop 1
	v_cndmask_b32_e32 v135, v206, v3, vcc
	v_cmp_lt_i32_e32 vcc, s8, v58
	s_nop 1
	v_cndmask_b32_e32 v136, v206, v2, vcc
	v_pk_mul_f32 v[2:3], v[6:7], s[20:21] op_sel_hi:[1,0]
	v_cmp_lt_i32_e32 vcc, s8, v51
	s_nop 1
	v_cndmask_b32_e32 v137, v206, v3, vcc
	v_cmp_lt_i32_e32 vcc, s8, v56
	s_nop 1
	v_cndmask_b32_e32 v138, v206, v2, vcc
	v_pk_mul_f32 v[2:3], v[12:13], s[20:21] op_sel_hi:[1,0]
	v_cmp_lt_i32_e32 vcc, s8, v57
	s_nop 1
	v_cndmask_b32_e32 v139, v206, v3, vcc
	v_cmp_lt_i32_e32 vcc, s8, v62
	s_nop 1
	v_cndmask_b32_e32 v140, v206, v2, vcc
	v_pk_mul_f32 v[2:3], v[10:11], s[20:21] op_sel_hi:[1,0]
	v_cmp_lt_i32_e32 vcc, s8, v55
	s_nop 1
	v_cndmask_b32_e32 v141, v206, v3, vcc
	v_cmp_lt_i32_e32 vcc, s8, v60
	s_nop 1
	v_cndmask_b32_e32 v142, v206, v2, vcc
	v_pk_mul_f32 v[2:3], v[16:17], s[20:21] op_sel_hi:[1,0]
	v_cmp_lt_i32_e32 vcc, s8, v61
	s_nop 1
	v_cndmask_b32_e32 v143, v206, v3, vcc
	v_cmp_lt_i32_e32 vcc, s8, v66
	s_nop 1
	v_cndmask_b32_e32 v144, v206, v2, vcc
	v_pk_mul_f32 v[2:3], v[14:15], s[20:21] op_sel_hi:[1,0]
	v_cmp_lt_i32_e32 vcc, s8, v59
	s_nop 1
	v_cndmask_b32_e32 v145, v206, v3, vcc
	v_cmp_lt_i32_e32 vcc, s8, v64
	s_nop 1
	v_cndmask_b32_e32 v159, v206, v2, vcc
	v_add_u32_e32 v2, s10, v41
	v_ashrrev_i32_e32 v3, 31, v2
	v_lshlrev_b64 v[2:3], 9, v[2:3]
	v_lshl_add_u64 v[126:127], v[34:35], 0, v[2:3]
	global_load_dwordx4 v[2:5], v[126:127], off
	global_load_dwordx4 v[122:125], v[126:127], off offset:32
	global_load_dwordx4 v[238:241], v[126:127], off offset:64
	global_load_dwordx4 v[242:245], v[126:127], off offset:96
	s_waitcnt vmcnt(3)
	v_mfma_f32_32x32x16_bf16 v[2:17], v[2:5], v[30:33], 0
	v_cmp_lt_i32_e32 vcc, s8, v65
	s_waitcnt vmcnt(2)
	v_mfma_f32_32x32x16_bf16 v[2:17], v[122:125], v[26:29], v[2:17]
	s_waitcnt vmcnt(1)
	v_mfma_f32_32x32x16_bf16 v[2:17], v[238:241], v[22:25], v[2:17]
	s_waitcnt vmcnt(0)
	v_mfma_f32_32x32x16_bf16 v[2:17], v[242:245], v[18:21], v[2:17]
	s_nop 11
	v_pk_mul_f32 v[4:5], v[4:5], s[20:21] op_sel_hi:[1,0]
	s_nop 0
	v_cndmask_b32_e32 v41, v206, v5, vcc
	v_cmp_lt_i32_e32 vcc, s8, v70
	v_pk_mul_f32 v[2:3], v[2:3], s[20:21] op_sel_hi:[1,0]
	s_nop 0
	v_cndmask_b32_e32 v160, v206, v4, vcc
	v_cmp_lt_i32_e32 vcc, s8, v63
	s_nop 1
	v_cndmask_b32_e32 v162, v206, v3, vcc
	v_cmp_lt_i32_e32 vcc, s8, v68
	s_nop 1
	v_cndmask_b32_e32 v168, v206, v2, vcc
	v_pk_mul_f32 v[2:3], v[8:9], s[20:21] op_sel_hi:[1,0]
	v_cmp_lt_i32_e32 vcc, s8, v69
	s_nop 1
	v_cndmask_b32_e32 v169, v206, v3, vcc
	v_cmp_lt_i32_e32 vcc, s8, v74
	s_nop 1
	v_cndmask_b32_e32 v170, v206, v2, vcc
	v_pk_mul_f32 v[2:3], v[6:7], s[20:21] op_sel_hi:[1,0]
	v_cmp_lt_i32_e32 vcc, s8, v67
	s_nop 1
	v_cndmask_b32_e32 v171, v206, v3, vcc
	v_cmp_lt_i32_e32 vcc, s8, v72
	s_nop 1
	v_cndmask_b32_e32 v172, v206, v2, vcc
	v_pk_mul_f32 v[2:3], v[12:13], s[20:21] op_sel_hi:[1,0]
	v_cmp_lt_i32_e32 vcc, s8, v73
	s_nop 1
	v_cndmask_b32_e32 v173, v206, v3, vcc
	v_cmp_lt_i32_e32 vcc, s8, v78
	s_nop 1
	v_cndmask_b32_e32 v179, v206, v2, vcc
	v_pk_mul_f32 v[2:3], v[10:11], s[20:21] op_sel_hi:[1,0]
	v_cmp_lt_i32_e32 vcc, s8, v71
	s_nop 1
	v_cndmask_b32_e32 v180, v206, v3, vcc
	v_cmp_lt_i32_e32 vcc, s8, v76
	s_nop 1
	v_cndmask_b32_e32 v181, v206, v2, vcc
	v_pk_mul_f32 v[2:3], v[16:17], s[20:21] op_sel_hi:[1,0]
	v_cmp_lt_i32_e32 vcc, s8, v77
	s_nop 1
	v_cndmask_b32_e32 v182, v206, v3, vcc
	v_cmp_lt_i32_e32 vcc, s8, v82
	s_nop 1
	v_cndmask_b32_e32 v183, v206, v2, vcc
	v_pk_mul_f32 v[2:3], v[14:15], s[20:21] op_sel_hi:[1,0]
	v_cmp_lt_i32_e32 vcc, s8, v75
	s_nop 1
	v_cndmask_b32_e32 v184, v206, v3, vcc
	v_cmp_lt_i32_e32 vcc, s8, v80
	s_nop 1
	v_cndmask_b32_e32 v185, v206, v2, vcc
	v_add_u32_e32 v2, s10, v120
	v_ashrrev_i32_e32 v3, 31, v2
	v_lshlrev_b64 v[2:3], 9, v[2:3]
	v_lshl_add_u64 v[126:127], v[34:35], 0, v[2:3]
	global_load_dwordx4 v[2:5], v[126:127], off
	global_load_dwordx4 v[122:125], v[126:127], off offset:32
	global_load_dwordx4 v[238:241], v[126:127], off offset:64
	global_load_dwordx4 v[242:245], v[126:127], off offset:96
	s_waitcnt vmcnt(3)
	v_mfma_f32_32x32x16_bf16 v[2:17], v[2:5], v[30:33], 0
	v_cmp_lt_i32_e32 vcc, s8, v81
	s_waitcnt vmcnt(2)
	v_mfma_f32_32x32x16_bf16 v[2:17], v[122:125], v[26:29], v[2:17]
	s_waitcnt vmcnt(1)
	v_mfma_f32_32x32x16_bf16 v[2:17], v[238:241], v[22:25], v[2:17]
	s_waitcnt vmcnt(0)
; __device__ __forceinline__ f32x16 mma32(bf16x8 a, bf16x8 b, f32x16 c) { return __builtin_amdgcn_mfma_f32_32x32x16_bf16(a, b, c, 0, 0, 0); }
; __device__ __forceinline__ int acc_row(int reg, int hh) { return (reg & 3) + 8 * (reg >> 2) + 4 * hh; }
; __device__ __forceinline__ void attn_prompt_task(const P& p, int l, int s, int qb, int h, LAS unsigned char* ldsw, int lane) {
;     ...
;     for (int kt = 0; kt < 5; ++kt) {
;         int pk = q0 - 128 + 32 * kt + r; pk = pk < 0 ? 0 : pk;
;         st[kt] = zero16();
; #pragma unroll
;         for (int ks = 0; ks < 4; ++ks) { const bf16x8 kf = *(const bf16x8*)(p.KB16 + (size_t)(s * TP + pk) * 256 + g * 64 + 16 * ks + 8 * hh); st[kt] = mma32(kf, qf[ks], st[kt]); }
;     }
;     const float sink = p.in[9][l * 16 + h];
;     float m = sink;
; #pragma unroll
;     for (int kt = 0; kt < 5; ++kt)
; #pragma unroll
;         for (int reg = 0; reg < 16; ++reg) {
;             const int kk = 32 * kt + acc_row(reg, hh);
;             const bool valid = (kk >= r) && (kk <= r + 128) && (q0 - 128 + kk >= 0);
;             const float v = valid ? st[kt][reg] * 0.125f : -3.0e38f;
;             st[kt][reg] = v; m = fmaxf(m, v);
;         }
;     m = fmaxf(m, __shfl_xor(m, 32));
	v_mfma_f32_32x32x16_bf16 v[2:17], v[242:245], v[18:21], v[2:17]
	s_nop 11
	v_pk_mul_f32 v[4:5], v[4:5], s[20:21] op_sel_hi:[1,0]
	s_nop 0
	v_cndmask_b32_e32 v120, v206, v5, vcc
	v_cmp_lt_i32_e32 vcc, s8, v86
	v_pk_mul_f32 v[2:3], v[2:3], s[20:21] op_sel_hi:[1,0]
	s_nop 0
	v_cndmask_b32_e32 v186, v206, v4, vcc
	v_cmp_lt_i32_e32 vcc, s8, v79
	s_nop 1
	v_cndmask_b32_e32 v187, v206, v3, vcc
	v_cmp_lt_i32_e32 vcc, s8, v84
	s_nop 1
	v_cndmask_b32_e32 v188, v206, v2, vcc
	v_pk_mul_f32 v[2:3], v[8:9], s[20:21] op_sel_hi:[1,0]
	v_cmp_lt_i32_e32 vcc, s8, v85
	s_nop 1
	v_cndmask_b32_e32 v189, v206, v3, vcc
	v_cmp_lt_i32_e32 vcc, s8, v90
	s_nop 1
	v_cndmask_b32_e32 v190, v206, v2, vcc
	v_pk_mul_f32 v[2:3], v[6:7], s[20:21] op_sel_hi:[1,0]
	v_cmp_lt_i32_e32 vcc, s8, v83
	s_nop 1
	v_cndmask_b32_e32 v191, v206, v3, vcc
	v_cmp_lt_i32_e32 vcc, s8, v88
	s_nop 1
	v_cndmask_b32_e32 v192, v206, v2, vcc
	v_pk_mul_f32 v[2:3], v[12:13], s[20:21] op_sel_hi:[1,0]
	v_cmp_lt_i32_e32 vcc, s8, v89
	s_nop 1
	v_cndmask_b32_e32 v193, v206, v3, vcc
	v_cmp_lt_i32_e32 vcc, s8, v94
	s_nop 1
	v_cndmask_b32_e32 v194, v206, v2, vcc
	v_pk_mul_f32 v[2:3], v[10:11], s[20:21] op_sel_hi:[1,0]
	v_cmp_lt_i32_e32 vcc, s8, v87
	s_nop 1
	v_cndmask_b32_e32 v195, v206, v3, vcc
	v_cmp_lt_i32_e32 vcc, s8, v92
	s_nop 1
	v_cndmask_b32_e32 v209, v206, v2, vcc
	v_pk_mul_f32 v[2:3], v[16:17], s[20:21] op_sel_hi:[1,0]
	v_cmp_lt_i32_e32 vcc, s8, v93
	s_nop 1
	v_cndmask_b32_e32 v210, v206, v3, vcc
	v_cmp_lt_i32_e32 vcc, s8, v98
	s_nop 1
	v_cndmask_b32_e32 v211, v206, v2, vcc
	v_pk_mul_f32 v[2:3], v[14:15], s[20:21] op_sel_hi:[1,0]
	v_cmp_lt_i32_e32 vcc, s8, v91
	s_nop 1
	v_cndmask_b32_e32 v212, v206, v3, vcc
	v_cmp_lt_i32_e32 vcc, s8, v96
	v_readlane_b32 s8, v248, 4
	v_readlane_b32 s9, v248, 5
	v_cndmask_b32_e32 v213, v206, v2, vcc
	v_lshlrev_b64 v[2:3], 9, v[112:113]
	v_lshl_add_u64 v[34:35], v[34:35], 0, v[2:3]
	global_load_dwordx4 v[2:5], v[34:35], off
	s_waitcnt vmcnt(0)
	v_mfma_f32_32x32x16_bf16 v[2:17], v[2:5], v[30:33], 0
	global_load_dwordx4 v[30:33], v[34:35], off offset:32
	v_cmp_lt_f32_e32 vcc, s17, v43
	s_waitcnt vmcnt(0)
	v_mfma_f32_32x32x16_bf16 v[2:17], v[30:33], v[26:29], v[2:17]
	global_load_dwordx4 v[26:29], v[34:35], off offset:64
	s_waitcnt vmcnt(0)
	v_mfma_f32_32x32x16_bf16 v[2:17], v[26:29], v[22:25], v[2:17]
	global_load_dwordx4 v[22:25], v[34:35], off offset:96
	s_waitcnt vmcnt(0)
	v_mfma_f32_32x32x16_bf16 v[2:17], v[22:25], v[18:21], v[2:17]
	s_nop 11
	v_pk_mul_f32 v[4:5], v[4:5], s[20:21] op_sel_hi:[1,0]
	s_nop 0
	v_cndmask_b32_e64 v5, v5, v206, s[8:9]
	v_readlane_b32 s8, v248, 6
	v_readlane_b32 s9, v248, 7
	v_pk_mul_f32 v[2:3], v[2:3], s[20:21] op_sel_hi:[1,0]
	v_pk_mul_f32 v[6:7], v[6:7], s[20:21] op_sel_hi:[1,0]
	v_cndmask_b32_e64 v4, v4, v206, s[8:9]
	v_readlane_b32 s8, v248, 2
	v_readlane_b32 s9, v248, 3
	v_cndmask_b32_e64 v2, v2, v206, s[90:91]
	v_pk_mul_f32 v[8:9], v[8:9], s[20:21] op_sel_hi:[1,0]
	v_cndmask_b32_e64 v3, v3, v206, s[8:9]
	v_readlane_b32 s8, v248, 8
	v_readlane_b32 s9, v248, 9
	v_pk_mul_f32 v[10:11], v[10:11], s[20:21] op_sel_hi:[1,0]
	v_cndmask_b32_e64 v18, v9, v206, s[46:47]
	v_cndmask_b32_e64 v34, v7, v206, s[8:9]
	v_readlane_b32 s8, v248, 10
	v_readlane_b32 s9, v248, 11
	v_cndmask_b32_e64 v19, v8, v206, s[48:49]
	v_pk_mul_f32 v[12:13], v[12:13], s[20:21] op_sel_hi:[1,0]
	v_cndmask_b32_e64 v35, v6, v206, s[8:9]
	v_max3_f32 v6, v37, v43, v45
	v_max3_f32 v6, v6, v105, v107
	v_max3_f32 v6, v6, v109, v114
	v_max3_f32 v6, v6, v115, v116
	v_max3_f32 v6, v6, v117, v118
	v_max3_f32 v6, v6, v119, v121
	v_max3_f32 v6, v6, v128, v129
	v_max3_f32 v6, v6, v130, v131
	v_max3_f32 v6, v6, v134, v133
	v_max3_f32 v6, v6, v132, v39
	v_max3_f32 v6, v6, v138, v137
	v_max3_f32 v6, v6, v136, v135
	v_max3_f32 v6, v6, v142, v141
	v_max3_f32 v6, v6, v140, v139
	v_max3_f32 v6, v6, v159, v145
	v_max3_f32 v6, v6, v144, v143
	v_max3_f32 v6, v6, v168, v162
	v_max3_f32 v6, v6, v160, v41
	v_max3_f32 v6, v6, v172, v171
	v_max3_f32 v6, v6, v170, v169
	v_max3_f32 v6, v6, v181, v180
	v_max3_f32 v6, v6, v179, v173
	v_max3_f32 v6, v6, v185, v184
	v_max3_f32 v6, v6, v183, v182
	v_max3_f32 v6, v6, v188, v187
	v_max3_f32 v6, v6, v186, v120
	v_max3_f32 v6, v6, v192, v191
	v_max3_f32 v6, v6, v190, v189
	v_max3_f32 v6, v6, v209, v195
	v_max3_f32 v6, v6, v194, v193
	v_max3_f32 v6, v6, v213, v212
	v_max3_f32 v6, v6, v211, v210
	v_max3_f32 v6, v6, v2, v3
	v_max3_f32 v6, v6, v4, v5
	v_max3_f32 v6, v6, v35, v34
	v_cndmask_b32_e64 v219, v11, v206, s[56:57]
	v_cndmask_b32_e64 v220, v10, v206, s[38:39]
	v_max3_f32 v6, v6, v19, v18
	v_pk_mul_f32 v[14:15], v[14:15], s[20:21] op_sel_hi:[1,0]
	v_cndmask_b32_e64 v112, v13, v206, s[40:41]
	v_cndmask_b32_e64 v113, v12, v206, s[42:43]
	v_max3_f32 v6, v6, v220, v219
	v_pk_mul_f32 v[16:17], v[16:17], s[20:21] op_sel_hi:[1,0]
	v_cndmask_b32_e64 v223, v15, v206, s[44:45]
	v_cndmask_b32_e64 v224, v14, v206, s[96:97]
	v_max3_f32 v6, v6, v113, v112
	v_cndmask_b32_e64 v225, v17, v206, s[0:1]
	v_cndmask_b32_e64 v226, v16, v206, s[4:5]
	v_max3_f32 v6, v6, v224, v223
	v_max3_f32 v6, v6, v226, v225
	ds_bpermute_b32 v7, v158, v6
	s_waitcnt lgkmcnt(0)
; __device__ __forceinline__ void attn_prompt_task(const P& p, int l, int s, int qb, int h, LAS unsigned char* ldsw, int lane) {
;     ...
;     m = fmaxf(m, __shfl_xor(m, 32));
;     float sum = 0.f;
; #pragma unroll
;     for (int kt = 0; kt < 5; ++kt)
; #pragma unroll
;         for (int reg = 0; reg < 16; ++reg) { const float e = st[kt][reg] > -1.0e38f ? __expf(st[kt][reg] - m) : 0.f; st[kt][reg] = e; sum += e; }
;     sum += __shfl_xor(sum, 32);
	v_max_f32_e32 v7, v7, v7
	v_max_f32_e32 v227, v6, v7
	v_sub_f32_e32 v6, v43, v227
	v_mul_f32_e32 v6, 0x3fb8aa3b, v6
	v_sub_f32_e32 v7, v45, v227
	v_exp_f32_e32 v6, v6
	v_mul_f32_e32 v7, 0x3fb8aa3b, v7
	v_sub_f32_e32 v8, v105, v227
	v_exp_f32_e32 v7, v7
	v_mul_f32_e32 v8, 0x3fb8aa3b, v8
	v_sub_f32_e32 v9, v107, v227
	v_exp_f32_e32 v8, v8
	v_mul_f32_e32 v9, 0x3fb8aa3b, v9
	v_sub_f32_e32 v10, v109, v227
	v_exp_f32_e32 v9, v9
	v_mul_f32_e32 v10, 0x3fb8aa3b, v10
	v_sub_f32_e32 v11, v114, v227
	v_cndmask_b32_e32 v6, 0, v6, vcc
	v_cmp_lt_f32_e32 vcc, s17, v45
	v_exp_f32_e32 v10, v10
	v_mul_f32_e32 v11, 0x3fb8aa3b, v11
	v_sub_f32_e32 v12, v115, v227
	v_cndmask_b32_e32 v7, 0, v7, vcc
	v_cmp_lt_f32_e32 vcc, s17, v105
	v_exp_f32_e32 v11, v11
	v_mul_f32_e32 v12, 0x3fb8aa3b, v12
	v_sub_f32_e32 v13, v116, v227
	v_cndmask_b32_e32 v8, 0, v8, vcc
	v_cmp_lt_f32_e32 vcc, s17, v107
	v_exp_f32_e32 v12, v12
	v_mul_f32_e32 v13, 0x3fb8aa3b, v13
	v_sub_f32_e32 v14, v117, v227
	v_cndmask_b32_e32 v9, 0, v9, vcc
	v_cmp_lt_f32_e32 vcc, s17, v109
	v_exp_f32_e32 v13, v13
	v_mul_f32_e32 v14, 0x3fb8aa3b, v14
	v_sub_f32_e32 v15, v118, v227
	v_cndmask_b32_e32 v10, 0, v10, vcc
	v_cmp_lt_f32_e32 vcc, s17, v114
	v_exp_f32_e32 v14, v14
	v_mul_f32_e32 v15, 0x3fb8aa3b, v15
	v_sub_f32_e32 v16, v119, v227
	v_cndmask_b32_e32 v11, 0, v11, vcc
	v_cmp_lt_f32_e32 vcc, s17, v115
	v_exp_f32_e32 v15, v15
	v_mul_f32_e32 v16, 0x3fb8aa3b, v16
	v_sub_f32_e32 v17, v121, v227
	v_cndmask_b32_e32 v12, 0, v12, vcc
	v_cmp_lt_f32_e32 vcc, s17, v116
	v_exp_f32_e32 v16, v16
	v_mul_f32_e32 v17, 0x3fb8aa3b, v17
	v_sub_f32_e32 v20, v128, v227
	v_cndmask_b32_e32 v13, 0, v13, vcc
	v_cmp_lt_f32_e32 vcc, s17, v117
	v_exp_f32_e32 v17, v17
	v_mul_f32_e32 v20, 0x3fb8aa3b, v20
	v_sub_f32_e32 v21, v129, v227
	v_cndmask_b32_e32 v14, 0, v14, vcc
	v_cmp_lt_f32_e32 vcc, s17, v118
	v_exp_f32_e32 v20, v20
	v_mul_f32_e32 v21, 0x3fb8aa3b, v21
	v_sub_f32_e32 v22, v130, v227
	v_cndmask_b32_e32 v15, 0, v15, vcc
	v_cmp_lt_f32_e32 vcc, s17, v119
	v_exp_f32_e32 v21, v21
	v_mul_f32_e32 v22, 0x3fb8aa3b, v22
	v_sub_f32_e32 v23, v131, v227
	v_cndmask_b32_e32 v16, 0, v16, vcc
	v_cmp_lt_f32_e32 vcc, s17, v121
	v_exp_f32_e32 v22, v22
	v_mul_f32_e32 v23, 0x3fb8aa3b, v23
	v_sub_f32_e32 v24, v133, v227
	v_cndmask_b32_e32 v17, 0, v17, vcc
	v_cmp_lt_f32_e32 vcc, s17, v128
	v_exp_f32_e32 v23, v23
	v_mul_f32_e32 v24, 0x3fb8aa3b, v24
	v_sub_f32_e32 v25, v134, v227
	v_cndmask_b32_e32 v20, 0, v20, vcc
	v_cmp_lt_f32_e32 vcc, s17, v129
	v_exp_f32_e32 v24, v24
	v_mul_f32_e32 v25, 0x3fb8aa3b, v25
	v_sub_f32_e32 v26, v39, v227
	v_cndmask_b32_e32 v21, 0, v21, vcc
	v_cmp_lt_f32_e32 vcc, s17, v130
	v_exp_f32_e32 v25, v25
	v_mul_f32_e32 v26, 0x3fb8aa3b, v26
	v_sub_f32_e32 v27, v132, v227
	v_cndmask_b32_e32 v22, 0, v22, vcc
	v_cmp_lt_f32_e32 vcc, s17, v131
	v_exp_f32_e32 v26, v26
	v_mul_f32_e32 v27, 0x3fb8aa3b, v27
	v_sub_f32_e32 v28, v137, v227
	v_cndmask_b32_e32 v23, 0, v23, vcc
	v_cmp_lt_f32_e32 vcc, s17, v133
	v_exp_f32_e32 v27, v27
	v_mul_f32_e32 v28, 0x3fb8aa3b, v28
	v_sub_f32_e32 v29, v138, v227
	v_cndmask_b32_e32 v24, 0, v24, vcc
	v_cmp_lt_f32_e32 vcc, s17, v134
	v_exp_f32_e32 v28, v28
	v_mul_f32_e32 v29, 0x3fb8aa3b, v29
	v_sub_f32_e32 v30, v135, v227
	v_cndmask_b32_e32 v25, 0, v25, vcc
	v_cmp_lt_f32_e32 vcc, s17, v39
	v_exp_f32_e32 v29, v29
	v_mul_f32_e32 v30, 0x3fb8aa3b, v30
	v_sub_f32_e32 v31, v136, v227
	v_cndmask_b32_e32 v26, 0, v26, vcc
	v_cmp_lt_f32_e32 vcc, s17, v132
	v_exp_f32_e32 v30, v30
	v_mul_f32_e32 v31, 0x3fb8aa3b, v31
	v_sub_f32_e32 v32, v141, v227
	v_cndmask_b32_e32 v27, 0, v27, vcc
	v_cmp_lt_f32_e32 vcc, s17, v137
	v_exp_f32_e32 v31, v31
	v_mul_f32_e32 v32, 0x3fb8aa3b, v32
	v_sub_f32_e32 v33, v142, v227
	v_cndmask_b32_e32 v28, 0, v28, vcc
	v_cmp_lt_f32_e32 vcc, s17, v138
	v_exp_f32_e32 v32, v32
	v_mul_f32_e32 v33, 0x3fb8aa3b, v33
	v_sub_f32_e32 v39, v139, v227
	v_cndmask_b32_e32 v29, 0, v29, vcc
	v_cmp_lt_f32_e32 vcc, s17, v135
	v_exp_f32_e32 v33, v33
	v_mul_f32_e32 v39, 0x3fb8aa3b, v39
	v_cndmask_b32_e32 v30, 0, v30, vcc
	v_cmp_lt_f32_e32 vcc, s17, v136
	v_exp_f32_e32 v39, v39
	v_ashrrev_i32_e32 v45, 31, v44
	v_cndmask_b32_e32 v31, 0, v31, vcc
	v_cmp_lt_f32_e32 vcc, s17, v141
	v_ashrrev_i32_e32 v43, 31, v42
	v_ashrrev_i32_e32 v105, 31, v104
	v_cndmask_b32_e32 v32, 0, v32, vcc
	v_cmp_lt_f32_e32 vcc, s17, v142
	v_ashrrev_i32_e32 v107, 31, v106
	v_ashrrev_i32_e32 v109, 31, v108
	v_cndmask_b32_e32 v33, 0, v33, vcc
	v_cmp_lt_f32_e32 vcc, s17, v139
	v_lshl_add_u64 v[114:115], v[42:43], 1, s[74:75]
	v_lshl_add_u64 v[106:107], v[106:107], 1, s[74:75]
	v_cndmask_b32_e32 v122, 0, v39, vcc
	v_sub_f32_e32 v39, v140, v227
	v_mul_f32_e32 v39, 0x3fb8aa3b, v39
	v_exp_f32_e32 v39, v39
	v_cmp_lt_f32_e32 vcc, s17, v140
	v_lshl_add_u64 v[140:141], v[44:45], 1, s[74:75]
	v_lshl_add_u64 v[42:43], v[114:115], 0, v[110:111]
	v_cndmask_b32_e32 v123, 0, v39, vcc
	v_sub_f32_e32 v39, v145, v227
	v_mul_f32_e32 v39, 0x3fb8aa3b, v39
	v_exp_f32_e32 v39, v39
	v_cmp_lt_f32_e32 vcc, s17, v145
	s_nop 1
	v_cndmask_b32_e32 v124, 0, v39, vcc
	v_sub_f32_e32 v39, v159, v227
	v_mul_f32_e32 v39, 0x3fb8aa3b, v39
	v_exp_f32_e32 v39, v39
	v_cmp_lt_f32_e32 vcc, s17, v159
	s_nop 1
	v_cndmask_b32_e32 v125, 0, v39, vcc
	v_sub_f32_e32 v39, v143, v227
	v_mul_f32_e32 v39, 0x3fb8aa3b, v39
	v_exp_f32_e32 v39, v39
	v_cmp_lt_f32_e32 vcc, s17, v143
	v_cvt_pk_bf16_f32 v228, v125, v124
	s_nop 0
	v_cndmask_b32_e32 v126, 0, v39, vcc
	v_sub_f32_e32 v39, v144, v227
	v_mul_f32_e32 v39, 0x3fb8aa3b, v39
	v_exp_f32_e32 v39, v39
	v_cmp_lt_f32_e32 vcc, s17, v144
	s_nop 1
	v_cndmask_b32_e32 v127, 0, v39, vcc
	v_sub_f32_e32 v39, v162, v227
	v_mul_f32_e32 v39, 0x3fb8aa3b, v39
	v_exp_f32_e32 v39, v39
; __device__ __forceinline__ void attn_prompt_task(const P& p, int l, int s, int qb, int h, LAS unsigned char* ldsw, int lane) {
;     ...
;     for (int kt = 0; kt < 5; ++kt)
; #pragma unroll
;         for (int reg = 0; reg < 16; ++reg) { const float e = st[kt][reg] > -1.0e38f ? __expf(st[kt][reg] - m) : 0.f; st[kt][reg] = e; sum += e; }
	v_cmp_lt_f32_e32 vcc, s17, v162
	v_cvt_pk_bf16_f32 v229, v127, v126
	s_nop 0
	v_cndmask_b32_e32 v128, 0, v39, vcc
	v_sub_f32_e32 v39, v168, v227
	v_mul_f32_e32 v39, 0x3fb8aa3b, v39
	v_exp_f32_e32 v39, v39
	v_cmp_lt_f32_e32 vcc, s17, v168
	s_nop 1
	v_cndmask_b32_e32 v129, 0, v39, vcc
	v_sub_f32_e32 v39, v41, v227
	v_mul_f32_e32 v39, 0x3fb8aa3b, v39
	v_exp_f32_e32 v39, v39
	v_cmp_lt_f32_e32 vcc, s17, v41
	v_ashrrev_i32_e32 v41, 31, v40
	s_nop 0
	v_cndmask_b32_e32 v130, 0, v39, vcc
	v_sub_f32_e32 v39, v160, v227
	v_mul_f32_e32 v39, 0x3fb8aa3b, v39
	v_exp_f32_e32 v39, v39
	v_cmp_lt_f32_e32 vcc, s17, v160
	s_nop 1
	v_cndmask_b32_e32 v131, 0, v39, vcc
	v_sub_f32_e32 v39, v171, v227
	v_mul_f32_e32 v39, 0x3fb8aa3b, v39
	v_exp_f32_e32 v39, v39
	v_cmp_lt_f32_e32 vcc, s17, v171
	s_nop 1
	v_cndmask_b32_e32 v132, 0, v39, vcc
	v_sub_f32_e32 v39, v172, v227
	v_mul_f32_e32 v39, 0x3fb8aa3b, v39
	v_exp_f32_e32 v39, v39
	v_cmp_lt_f32_e32 vcc, s17, v172
	v_or_b32_e32 v172, 0x40000, v110
	s_nop 0
	v_cndmask_b32_e32 v133, 0, v39, vcc
	v_sub_f32_e32 v39, v169, v227
	v_mul_f32_e32 v39, 0x3fb8aa3b, v39
	v_exp_f32_e32 v39, v39
	v_cmp_lt_f32_e32 vcc, s17, v169
	v_lshl_add_u64 v[168:169], v[104:105], 1, s[74:75]
	s_nop 0
	v_cndmask_b32_e32 v134, 0, v39, vcc
	v_sub_f32_e32 v39, v170, v227
	v_mul_f32_e32 v39, 0x3fb8aa3b, v39
	v_exp_f32_e32 v39, v39
	v_cmp_lt_f32_e32 vcc, s17, v170
	v_lshl_add_u64 v[170:171], v[108:109], 1, s[74:75]
	v_lshl_add_u64 v[108:109], v[170:171], 0, v[110:111]
	v_cndmask_b32_e32 v135, 0, v39, vcc
	v_sub_f32_e32 v39, v180, v227
	v_mul_f32_e32 v39, 0x3fb8aa3b, v39
	v_exp_f32_e32 v39, v39
	v_cmp_lt_f32_e32 vcc, s17, v180
	s_nop 1
	v_cndmask_b32_e32 v136, 0, v39, vcc
	v_sub_f32_e32 v39, v181, v227
	v_mul_f32_e32 v39, 0x3fb8aa3b, v39
	v_exp_f32_e32 v39, v39
	v_cmp_lt_f32_e32 vcc, s17, v181
	s_nop 1
	v_cndmask_b32_e32 v137, 0, v39, vcc
	v_sub_f32_e32 v39, v173, v227
	v_mul_f32_e32 v39, 0x3fb8aa3b, v39
	v_exp_f32_e32 v39, v39
	v_cmp_lt_f32_e32 vcc, s17, v173
	v_mov_b32_e32 v173, v111
	v_cvt_pk_bf16_f32 v142, v137, v136
	v_cndmask_b32_e32 v143, 0, v39, vcc
	v_sub_f32_e32 v39, v179, v227
	v_mul_f32_e32 v39, 0x3fb8aa3b, v39
	v_exp_f32_e32 v39, v39
	v_cmp_lt_f32_e32 vcc, s17, v179
	v_lshl_add_u64 v[44:45], v[114:115], 0, v[172:173]
	v_lshl_add_u64 v[114:115], v[106:107], 0, v[172:173]
	v_cndmask_b32_e32 v144, 0, v39, vcc
	v_sub_f32_e32 v39, v184, v227
	v_mul_f32_e32 v39, 0x3fb8aa3b, v39
	v_exp_f32_e32 v39, v39
	v_cmp_lt_f32_e32 vcc, s17, v184
	s_nop 1
	v_cndmask_b32_e32 v145, 0, v39, vcc
	v_sub_f32_e32 v39, v185, v227
	v_mul_f32_e32 v39, 0x3fb8aa3b, v39
	v_exp_f32_e32 v39, v39
	v_cmp_lt_f32_e32 vcc, s17, v185
	s_nop 1
	v_cndmask_b32_e32 v179, 0, v39, vcc
	v_sub_f32_e32 v39, v182, v227
	v_mul_f32_e32 v39, 0x3fb8aa3b, v39
	v_exp_f32_e32 v39, v39
	v_cmp_lt_f32_e32 vcc, s17, v182
	s_nop 1
	v_cndmask_b32_e32 v180, 0, v39, vcc
	v_sub_f32_e32 v39, v183, v227
	v_mul_f32_e32 v39, 0x3fb8aa3b, v39
	v_exp_f32_e32 v39, v39
	v_cmp_lt_f32_e32 vcc, s17, v183
	s_nop 1
	v_cndmask_b32_e32 v181, 0, v39, vcc
	v_sub_f32_e32 v39, v187, v227
	v_mul_f32_e32 v39, 0x3fb8aa3b, v39
	v_exp_f32_e32 v39, v39
	v_cmp_lt_f32_e32 vcc, s17, v187
	s_nop 1
	v_cndmask_b32_e32 v182, 0, v39, vcc
	v_sub_f32_e32 v39, v188, v227
	v_mul_f32_e32 v39, 0x3fb8aa3b, v39
	v_exp_f32_e32 v39, v39
	v_cmp_lt_f32_e32 vcc, s17, v188
	s_nop 1
	v_cndmask_b32_e32 v183, 0, v39, vcc
	v_sub_f32_e32 v39, v120, v227
	v_mul_f32_e32 v39, 0x3fb8aa3b, v39
	v_exp_f32_e32 v39, v39
	v_cmp_lt_f32_e32 vcc, s17, v120
	s_nop 1
	v_cndmask_b32_e32 v184, 0, v39, vcc
	v_sub_f32_e32 v39, v186, v227
	v_mul_f32_e32 v39, 0x3fb8aa3b, v39
	v_exp_f32_e32 v39, v39
	v_cmp_lt_f32_e32 vcc, s17, v186
	s_nop 1
	v_cndmask_b32_e32 v185, 0, v39, vcc
	v_sub_f32_e32 v39, v191, v227
	v_mul_f32_e32 v39, 0x3fb8aa3b, v39
	v_exp_f32_e32 v39, v39
	v_cmp_lt_f32_e32 vcc, s17, v191
	s_nop 1
	v_cndmask_b32_e32 v186, 0, v39, vcc
	v_sub_f32_e32 v39, v192, v227
	v_mul_f32_e32 v39, 0x3fb8aa3b, v39
	v_exp_f32_e32 v39, v39
	v_cmp_lt_f32_e32 vcc, s17, v192
	s_nop 1
	v_cndmask_b32_e32 v187, 0, v39, vcc
	v_sub_f32_e32 v39, v189, v227
	v_mul_f32_e32 v39, 0x3fb8aa3b, v39
	v_exp_f32_e32 v39, v39
	v_cmp_lt_f32_e32 vcc, s17, v189
	s_nop 1
	v_cndmask_b32_e32 v188, 0, v39, vcc
	v_sub_f32_e32 v39, v190, v227
	v_mul_f32_e32 v39, 0x3fb8aa3b, v39
	v_exp_f32_e32 v39, v39
	v_cmp_lt_f32_e32 vcc, s17, v190
	s_nop 1
	v_cndmask_b32_e32 v189, 0, v39, vcc
	v_sub_f32_e32 v39, v195, v227
	v_mul_f32_e32 v39, 0x3fb8aa3b, v39
	v_exp_f32_e32 v39, v39
	v_cmp_lt_f32_e32 vcc, s17, v195
	s_nop 1
	v_cndmask_b32_e32 v190, 0, v39, vcc
	v_sub_f32_e32 v39, v209, v227
	v_mul_f32_e32 v39, 0x3fb8aa3b, v39
	v_exp_f32_e32 v39, v39
	v_cmp_lt_f32_e32 vcc, s17, v209
	s_nop 1
	v_cndmask_b32_e32 v191, 0, v39, vcc
	v_sub_f32_e32 v39, v193, v227
	v_mul_f32_e32 v39, 0x3fb8aa3b, v39
	v_exp_f32_e32 v39, v39
	v_cmp_lt_f32_e32 vcc, s17, v193
	s_nop 1
	v_cndmask_b32_e32 v192, 0, v39, vcc
	v_sub_f32_e32 v39, v194, v227
	v_mul_f32_e32 v39, 0x3fb8aa3b, v39
	v_exp_f32_e32 v39, v39
	v_cmp_lt_f32_e32 vcc, s17, v194
	s_nop 1
	v_cndmask_b32_e32 v193, 0, v39, vcc
	v_sub_f32_e32 v39, v212, v227
	v_mul_f32_e32 v39, 0x3fb8aa3b, v39
	v_exp_f32_e32 v39, v39
	v_cmp_lt_f32_e32 vcc, s17, v212
	s_nop 1
	v_cndmask_b32_e32 v194, 0, v39, vcc
	v_sub_f32_e32 v39, v213, v227
	v_mul_f32_e32 v39, 0x3fb8aa3b, v39
	v_exp_f32_e32 v39, v39
	v_cmp_lt_f32_e32 vcc, s17, v213
	s_nop 1
	v_cndmask_b32_e32 v195, 0, v39, vcc
	v_sub_f32_e32 v39, v210, v227
	v_mul_f32_e32 v39, 0x3fb8aa3b, v39
	v_exp_f32_e32 v39, v39
	v_cmp_lt_f32_e32 vcc, s17, v210
	s_nop 1
	v_cndmask_b32_e32 v209, 0, v39, vcc
	v_sub_f32_e32 v39, v211, v227
	v_mul_f32_e32 v39, 0x3fb8aa3b, v39
; __device__ __forceinline__ unsigned pk2(float lo, float hi) { f32x2_t v = {lo, hi}; bf16x2_t b = __builtin_convertvector(v, bf16x2_t); return __builtin_bit_cast(unsigned, b); }
; #define LAS __attribute__((address_space(3)))
; #define LDS_WAIT() asm volatile("s_waitcnt lgkmcnt(0)" ::: "memory")
; __device__ __forceinline__ void attn_prompt_task(const P& p, int l, int s, int qb, int h, LAS unsigned char* ldsw, int lane) {
;     ...
;     for (int kt = 0; kt < 5; ++kt)
; #pragma unroll
;         for (int reg = 0; reg < 16; ++reg) { const float e = st[kt][reg] > -1.0e38f ? __expf(st[kt][reg] - m) : 0.f; st[kt][reg] = e; sum += e; }
;     sum += __shfl_xor(sum, 32);
;     const float inv = 1.f / (sum + __expf(sink - m));
;     f32x16 o[2]; o[0] = zero16(); o[1] = zero16();
; #pragma unroll
;     for (int kt = 0; kt < 5; ++kt) {
; #pragma unroll
;         for (int gq = 0; gq < 4; ++gq) { u32x2v w; w.x = pk2(st[kt][4 * gq], st[kt][4 * gq + 1]); w.y = pk2(st[kt][4 * gq + 2], st[kt][4 * gq + 3]); *(LAS u32x2v*)(PT + r * 40 + 8 * gq + 4 * hh) = w; }
;         LDS_WAIT();
	v_exp_f32_e32 v39, v39
	v_cmp_lt_f32_e32 vcc, s17, v211
	s_nop 1
	v_cndmask_b32_e32 v210, 0, v39, vcc
	v_sub_f32_e32 v39, v3, v227
	v_mul_f32_e32 v39, 0x3fb8aa3b, v39
	v_exp_f32_e32 v39, v39
	v_cmp_lt_f32_e32 vcc, s17, v3
	v_sub_f32_e32 v3, v2, v227
	v_mul_f32_e32 v3, 0x3fb8aa3b, v3
	v_cndmask_b32_e32 v211, 0, v39, vcc
	v_cmp_lt_f32_e32 vcc, s17, v2
	v_sub_f32_e32 v2, v5, v227
	v_exp_f32_e32 v3, v3
	v_mul_f32_e32 v2, 0x3fb8aa3b, v2
	v_exp_f32_e32 v2, v2
	v_ashrrev_i32_e32 v39, 31, v38
	v_cndmask_b32_e32 v212, 0, v3, vcc
	v_cmp_lt_f32_e32 vcc, s17, v5
	v_add_f32_e32 v3, 0, v6
	v_add_f32_e32 v3, v7, v3
	v_cndmask_b32_e32 v213, 0, v2, vcc
	v_sub_f32_e32 v2, v4, v227
	v_mul_f32_e32 v2, 0x3fb8aa3b, v2
	v_exp_f32_e32 v2, v2
	v_add_f32_e32 v3, v8, v3
	v_add_f32_e32 v3, v9, v3
	v_cmp_lt_f32_e32 vcc, s17, v4
	v_add_f32_e32 v3, v10, v3
	v_add_f32_e32 v3, v11, v3
	v_cndmask_b32_e32 v214, 0, v2, vcc
	v_sub_f32_e32 v2, v34, v227
	v_mul_f32_e32 v2, 0x3fb8aa3b, v2
	v_add_f32_e32 v3, v12, v3
	v_exp_f32_e32 v2, v2
	v_add_f32_e32 v3, v13, v3
	v_add_f32_e32 v3, v14, v3
	v_add_f32_e32 v3, v15, v3
	v_cmp_lt_f32_e32 vcc, s17, v34
	v_add_f32_e32 v3, v16, v3
	v_add_f32_e32 v3, v17, v3
	v_cndmask_b32_e32 v215, 0, v2, vcc
	v_sub_f32_e32 v2, v35, v227
	v_mul_f32_e32 v2, 0x3fb8aa3b, v2
	v_add_f32_e32 v3, v20, v3
	v_exp_f32_e32 v2, v2
	v_add_f32_e32 v3, v21, v3
	v_add_f32_e32 v3, v22, v3
	v_add_f32_e32 v3, v23, v3
	v_cmp_lt_f32_e32 vcc, s17, v35
	v_add_f32_e32 v3, v25, v3
	v_add_f32_e32 v3, v24, v3
	v_cndmask_b32_e32 v216, 0, v2, vcc
	v_sub_f32_e32 v2, v18, v227
	v_mul_f32_e32 v2, 0x3fb8aa3b, v2
	v_add_f32_e32 v3, v27, v3
	v_exp_f32_e32 v2, v2
	v_add_f32_e32 v3, v26, v3
	v_add_f32_e32 v3, v29, v3
	v_add_f32_e32 v3, v28, v3
	v_cmp_lt_f32_e32 vcc, s17, v18
	v_add_f32_e32 v3, v31, v3
	v_add_f32_e32 v3, v30, v3
	v_cndmask_b32_e32 v217, 0, v2, vcc
	v_sub_f32_e32 v2, v19, v227
	v_mul_f32_e32 v2, 0x3fb8aa3b, v2
	v_add_f32_e32 v3, v33, v3
	v_exp_f32_e32 v2, v2
	v_add_f32_e32 v3, v32, v3
	v_add_f32_e32 v3, v123, v3
	v_add_f32_e32 v3, v122, v3
	v_cmp_lt_f32_e32 vcc, s17, v19
	v_add_f32_e32 v3, v125, v3
	v_add_f32_e32 v3, v124, v3
	v_cndmask_b32_e32 v218, 0, v2, vcc
	v_sub_f32_e32 v2, v219, v227
	v_mul_f32_e32 v2, 0x3fb8aa3b, v2
	v_add_f32_e32 v3, v127, v3
	v_exp_f32_e32 v2, v2
	v_add_f32_e32 v3, v126, v3
	v_add_f32_e32 v3, v129, v3
	v_add_f32_e32 v3, v128, v3
	v_cmp_lt_f32_e32 vcc, s17, v219
	v_add_f32_e32 v3, v131, v3
	v_add_f32_e32 v3, v130, v3
	v_cndmask_b32_e32 v219, 0, v2, vcc
	v_sub_f32_e32 v2, v220, v227
	v_mul_f32_e32 v2, 0x3fb8aa3b, v2
	v_add_f32_e32 v3, v133, v3
	v_exp_f32_e32 v2, v2
	v_add_f32_e32 v3, v132, v3
	v_add_f32_e32 v3, v135, v3
	v_add_f32_e32 v3, v134, v3
	v_cmp_lt_f32_e32 vcc, s17, v220
	v_add_f32_e32 v3, v137, v3
	v_add_f32_e32 v3, v136, v3
	v_cndmask_b32_e32 v220, 0, v2, vcc
	v_sub_f32_e32 v2, v112, v227
	v_mul_f32_e32 v2, 0x3fb8aa3b, v2
	v_add_f32_e32 v3, v144, v3
	v_exp_f32_e32 v2, v2
	v_add_f32_e32 v3, v143, v3
	v_add_f32_e32 v3, v179, v3
	v_add_f32_e32 v3, v145, v3
	v_cmp_lt_f32_e32 vcc, s17, v112
	v_add_f32_e32 v3, v181, v3
	v_add_f32_e32 v3, v180, v3
	v_cndmask_b32_e32 v221, 0, v2, vcc
	v_sub_f32_e32 v2, v113, v227
	v_mul_f32_e32 v2, 0x3fb8aa3b, v2
	v_add_f32_e32 v3, v183, v3
	v_exp_f32_e32 v2, v2
	v_add_f32_e32 v3, v182, v3
	v_add_f32_e32 v3, v185, v3
	v_add_f32_e32 v3, v184, v3
	v_cmp_lt_f32_e32 vcc, s17, v113
	v_add_f32_e32 v3, v187, v3
	v_add_f32_e32 v3, v186, v3
	v_cndmask_b32_e32 v222, 0, v2, vcc
	v_sub_f32_e32 v2, v223, v227
	v_mul_f32_e32 v2, 0x3fb8aa3b, v2
	v_add_f32_e32 v3, v189, v3
	v_exp_f32_e32 v2, v2
	v_add_f32_e32 v3, v188, v3
	v_add_f32_e32 v3, v191, v3
	v_add_f32_e32 v3, v190, v3
	v_cmp_lt_f32_e32 vcc, s17, v223
	v_add_f32_e32 v3, v193, v3
	v_add_f32_e32 v3, v192, v3
	v_cndmask_b32_e32 v223, 0, v2, vcc
	v_sub_f32_e32 v2, v224, v227
	v_mul_f32_e32 v2, 0x3fb8aa3b, v2
	v_add_f32_e32 v3, v195, v3
	v_exp_f32_e32 v2, v2
	v_add_f32_e32 v3, v194, v3
	v_add_f32_e32 v3, v210, v3
	v_add_f32_e32 v3, v209, v3
	v_cmp_lt_f32_e32 vcc, s17, v224
	v_add_f32_e32 v3, v212, v3
	v_add_f32_e32 v3, v211, v3
	v_cndmask_b32_e32 v224, 0, v2, vcc
	v_sub_f32_e32 v2, v225, v227
	v_mul_f32_e32 v2, 0x3fb8aa3b, v2
	v_add_f32_e32 v3, v214, v3
	v_exp_f32_e32 v2, v2
	v_add_f32_e32 v3, v213, v3
	v_add_f32_e32 v3, v216, v3
	v_add_f32_e32 v3, v215, v3
	v_cmp_lt_f32_e32 vcc, s17, v225
	v_add_f32_e32 v3, v218, v3
	v_add_f32_e32 v3, v217, v3
	v_cndmask_b32_e32 v225, 0, v2, vcc
	v_sub_f32_e32 v2, v226, v227
	v_mul_f32_e32 v2, 0x3fb8aa3b, v2
	v_add_f32_e32 v3, v220, v3
	v_exp_f32_e32 v2, v2
	v_add_f32_e32 v3, v219, v3
	v_add_f32_e32 v3, v222, v3
	v_add_f32_e32 v3, v221, v3
	v_cmp_lt_f32_e32 vcc, s17, v226
	v_add_f32_e32 v3, v224, v3
	v_add_f32_e32 v3, v223, v3
	v_cndmask_b32_e32 v226, 0, v2, vcc
	v_add_f32_e32 v3, v226, v3
	v_add_f32_e32 v3, v225, v3
	v_sub_f32_e32 v2, v37, v227
	ds_bpermute_b32 v4, v158, v3
	v_mul_f32_e32 v2, 0x3fb8aa3b, v2
	v_exp_f32_e32 v2, v2
	v_ashrrev_i32_e32 v37, 31, v36
	v_cvt_pk_bf16_f32 v6, v6, v7
	s_waitcnt lgkmcnt(0)
	v_add_f32_e32 v3, v3, v4
	v_add_f32_e32 v159, v2, v3
	v_div_scale_f32 v2, s[8:9], v159, v159, 1.0
	v_rcp_f32_e32 v3, v2
	v_cvt_pk_bf16_f32 v7, v8, v9
	v_cvt_pk_bf16_f32 v8, v10, v11
	v_cvt_pk_bf16_f32 v9, v12, v13
	v_fma_f32 v4, -v2, v3, 1.0
	v_fmac_f32_e32 v3, v4, v3
	v_div_scale_f32 v4, vcc, 1.0, v159, 1.0
	v_mul_f32_e32 v5, v4, v3
	v_fma_f32 v18, -v2, v5, v4
	v_fmac_f32_e32 v5, v18, v3
	v_fma_f32 v2, -v2, v5, v4
	v_div_fmas_f32 v160, v2, v3, v5
	v_or_b32_e32 v2, s7, v46
	v_lshl_add_u64 v[4:5], v[36:37], 1, s[74:75]
	v_cvt_pk_bf16_f32 v10, v14, v15
	v_cvt_pk_bf16_f32 v11, v16, v17
	v_cvt_pk_bf16_f32 v12, v20, v21
	v_cvt_pk_bf16_f32 v13, v22, v23
	ds_write2_b64 v157, v[6:7], v[8:9] offset1:2
	ds_write2_b64 v157, v[10:11], v[12:13] offset0:4 offset1:6
	v_lshlrev_b32_e32 v162, 1, v2
	v_lshl_add_u64 v[2:3], v[4:5], 0, v[110:111]
	s_waitcnt lgkmcnt(0)
; __device__ __forceinline__ unsigned pk2(float lo, float hi) { f32x2_t v = {lo, hi}; bf16x2_t b = __builtin_convertvector(v, bf16x2_t); return __builtin_bit_cast(unsigned, b); }
; #define LAS __attribute__((address_space(3)))
; __device__ __forceinline__ f32x16 mma32(bf16x8 a, bf16x8 b, f32x16 c) { return __builtin_amdgcn_mfma_f32_32x32x16_bf16(a, b, c, 0, 0, 0); }
; #define LDS_WAIT() asm volatile("s_waitcnt lgkmcnt(0)" ::: "memory")
; __device__ __forceinline__ void attn_prompt_task(const P& p, int l, int s, int qb, int h, LAS unsigned char* ldsw, int lane) {
;     ...
; #pragma unroll
;     for (int kt = 0; kt < 5; ++kt) {
; #pragma unroll
;         for (int gq = 0; gq < 4; ++gq) { u32x2v w; w.x = pk2(st[kt][4 * gq], st[kt][4 * gq + 1]); w.y = pk2(st[kt][4 * gq + 2], st[kt][4 * gq + 3]); *(LAS u32x2v*)(PT + r * 40 + 8 * gq + 4 * hh) = w; }
;         LDS_WAIT();
; #pragma unroll
;         for (int ks = 0; ks < 2; ++ks) {
;             const bf16x8 pf = *(const LAS bf16x8*)(PT + r * 40 + 16 * ks + 8 * hh);
;             int p0 = q0 - 128 + 32 * kt + 16 * ks + 8 * hh; p0 = p0 < 0 ? 0 : p0;
; #pragma unroll
;             for (int dt = 0; dt < 2; ++dt) { const bf16x8 vf = *(const bf16x8*)(p.VT16 + ((size_t)(s * 4 + g) * 64 + 32 * dt + r) * TP + p0); o[dt] = mma32(vf, pf, o[dt]); }
;         }
;         LDS_WAIT();
;     }
	v_lshl_add_u64 v[4:5], v[4:5], 0, v[172:173]
	global_load_dwordx4 v[6:9], v[2:3], off
	global_load_dwordx4 v[20:23], v[4:5], off
	v_lshl_add_u64 v[36:37], v[38:39], 1, s[74:75]
	v_lshl_add_u64 v[38:39], v[40:41], 1, s[74:75]
	v_lshl_add_u64 v[18:19], v[36:37], 0, v[110:111]
	v_lshl_add_u64 v[118:119], v[38:39], 0, v[110:111]
	v_lshl_add_u64 v[40:41], v[140:141], 0, v[110:111]
	v_lshl_add_u64 v[116:117], v[38:39], 0, v[172:173]
	v_lshl_add_u64 v[38:39], v[140:141], 0, v[172:173]
	v_cvt_pk_bf16_f32 v141, v135, v134
	v_cvt_pk_bf16_f32 v143, v144, v143
	v_cvt_pk_bf16_f32 v144, v179, v145
	v_cvt_pk_bf16_f32 v145, v181, v180
	v_cvt_pk_bf16_f32 v134, v183, v182
	global_load_dwordx4 v[180:183], v[18:19], off
	v_lshl_add_u64 v[120:121], v[36:37], 0, v[172:173]
	v_cvt_pk_bf16_f32 v135, v185, v184
	v_cvt_pk_bf16_f32 v136, v187, v186
	global_load_dwordx4 v[184:187], v[120:121], off
	v_lshl_add_u64 v[138:139], s[74:75], 0, v[162:163]
	v_lshl_add_u64 v[34:35], v[168:169], 0, v[110:111]
	v_lshl_add_u64 v[112:113], v[106:107], 0, v[110:111]
	v_lshl_add_u64 v[104:105], v[138:139], 0, v[110:111]
	v_lshl_add_u64 v[36:37], v[168:169], 0, v[172:173]
	v_lshl_add_u64 v[110:111], v[170:171], 0, v[172:173]
	v_add_u32_e32 v162, v157, v46
	v_cvt_pk_bf16_f32 v168, v25, v24
	v_cvt_pk_bf16_f32 v169, v27, v26
	v_cvt_pk_bf16_f32 v170, v29, v28
	v_cvt_pk_bf16_f32 v171, v31, v30
	v_lshl_add_u64 v[106:107], v[138:139], 0, v[172:173]
	v_cvt_pk_bf16_f32 v172, v33, v32
	v_cvt_pk_bf16_f32 v173, v123, v122
	v_cvt_pk_bf16_f32 v139, v131, v130
	v_cvt_pk_bf16_f32 v137, v189, v188
	v_cvt_pk_bf16_f32 v130, v191, v190
	ds_read_b128 v[24:27], v162
	ds_read_b128 v[188:191], v162 offset:32
	s_waitcnt lgkmcnt(0)
	ds_write2_b64 v157, v[168:169], v[170:171] offset1:2
	ds_write2_b64 v157, v[172:173], v[228:229] offset0:4 offset1:6
	s_waitcnt lgkmcnt(0)
	global_load_dwordx4 v[118:121], v[118:119], off
	s_waitcnt vmcnt(4) lgkmcnt(3)
	v_mfma_f32_32x32x16_bf16 v[2:17], v[6:9], v[24:27], 0
	v_cvt_pk_bf16_f32 v138, v129, v128
	v_cvt_pk_bf16_f32 v140, v133, v132
	v_cvt_pk_bf16_f32 v131, v193, v192
	v_cvt_pk_bf16_f32 v132, v195, v194
	v_cvt_pk_bf16_f32 v133, v210, v209
	v_cvt_pk_bf16_f32 v126, v212, v211
	v_cvt_pk_bf16_f32 v127, v214, v213
	s_waitcnt vmcnt(3)
	v_mfma_f32_32x32x16_bf16 v[18:33], v[20:23], v[24:27], 0
	v_cvt_pk_bf16_f32 v128, v216, v215
	v_cvt_pk_bf16_f32 v129, v218, v217
	v_cvt_pk_bf16_f32 v122, v220, v219
	v_cvt_pk_bf16_f32 v123, v222, v221
	v_cvt_pk_bf16_f32 v124, v224, v223
	v_cvt_pk_bf16_f32 v125, v226, v225
	s_waitcnt vmcnt(2) lgkmcnt(2)
	v_mfma_f32_32x32x16_bf16 v[2:17], v[180:183], v[188:191], v[2:17]
	global_load_dwordx4 v[180:183], v[116:117], off
	s_waitcnt vmcnt(2)
	v_mfma_f32_32x32x16_bf16 v[18:33], v[184:187], v[188:191], v[18:33]
	ds_read_b128 v[184:187], v162
	s_waitcnt vmcnt(1) lgkmcnt(0)
	v_mfma_f32_32x32x16_bf16 v[2:17], v[118:121], v[184:187], v[2:17]
	global_load_dwordx4 v[116:119], v[42:43], off
	s_nop 0
	global_load_dwordx4 v[42:45], v[44:45], off
	s_waitcnt vmcnt(2)
	v_mfma_f32_32x32x16_bf16 v[18:33], v[180:183], v[184:187], v[18:33]
	ds_read_b128 v[180:183], v162 offset:32
	s_waitcnt lgkmcnt(0)
	ds_write2_b64 v157, v[138:139], v[140:141] offset1:2
	ds_write2_b64 v157, v[142:143], v[144:145] offset0:4 offset1:6
	s_waitcnt lgkmcnt(0)
	ds_read_b128 v[138:141], v162
	s_waitcnt vmcnt(1) lgkmcnt(3)
	v_mfma_f32_32x32x16_bf16 v[2:17], v[116:119], v[180:183], v[2:17]
	global_load_dwordx4 v[116:119], v[40:41], off
	s_waitcnt vmcnt(1)
	v_mfma_f32_32x32x16_bf16 v[18:33], v[42:45], v[180:183], v[18:33]
	global_load_dwordx4 v[42:45], v[38:39], off
	s_nop 0
	global_load_dwordx4 v[38:41], v[34:35], off
	s_nop 0
	global_load_dwordx4 v[34:37], v[36:37], off
	s_waitcnt vmcnt(3) lgkmcnt(0)
	v_mfma_f32_32x32x16_bf16 v[2:17], v[116:119], v[138:141], v[2:17]
	s_waitcnt vmcnt(2)
	v_mfma_f32_32x32x16_bf16 v[18:33], v[42:45], v[138:141], v[18:33]
	ds_read_b128 v[42:45], v162 offset:32
	s_waitcnt lgkmcnt(0)
; __device__ __forceinline__ unsigned pk2(float lo, float hi) { f32x2_t v = {lo, hi}; bf16x2_t b = __builtin_convertvector(v, bf16x2_t); return __builtin_bit_cast(unsigned, b); }
; #define LAS __attribute__((address_space(3)))
; __device__ __forceinline__ f32x16 mma32(bf16x8 a, bf16x8 b, f32x16 c) { return __builtin_amdgcn_mfma_f32_32x32x16_bf16(a, b, c, 0, 0, 0); }
; #define LDS_WAIT() asm volatile("s_waitcnt lgkmcnt(0)" ::: "memory")
; __device__ __forceinline__ void attn_prompt_task(const P& p, int l, int s, int qb, int h, LAS unsigned char* ldsw, int lane) {
;     ...
;     for (int kt = 0; kt < 5; ++kt) {
; #pragma unroll
;         for (int gq = 0; gq < 4; ++gq) { u32x2v w; w.x = pk2(st[kt][4 * gq], st[kt][4 * gq + 1]); w.y = pk2(st[kt][4 * gq + 2], st[kt][4 * gq + 3]); *(LAS u32x2v*)(PT + r * 40 + 8 * gq + 4 * hh) = w; }
;         LDS_WAIT();
; #pragma unroll
;         for (int ks = 0; ks < 2; ++ks) {
;             const bf16x8 pf = *(const LAS bf16x8*)(PT + r * 40 + 16 * ks + 8 * hh);
;             int p0 = q0 - 128 + 32 * kt + 16 * ks + 8 * hh; p0 = p0 < 0 ? 0 : p0;
; #pragma unroll
;             for (int dt = 0; dt < 2; ++dt) { const bf16x8 vf = *(const bf16x8*)(p.VT16 + ((size_t)(s * 4 + g) * 64 + 32 * dt + r) * TP + p0); o[dt] = mma32(vf, pf, o[dt]); }
;         }
;         LDS_WAIT();
;     }
; #pragma unroll
;     for (int dt = 0; dt < 2; ++dt)
; #pragma unroll
;         for (int gq = 0; gq < 4; ++gq) { u32x2v w; w.x = pk2(o[dt][4 * gq] * inv, o[dt][4 * gq + 1] * inv); w.y = pk2(o[dt][4 * gq + 2] * inv, o[dt][4 * gq + 3] * inv);
;             *(u32x2v*)(p.OAb + (size_t)(s * TP + q0 + r) * 1024 + h * 64 + 32 * dt + 8 * gq + 4 * hh) = w; }
	ds_write2_b64 v157, v[134:135], v[136:137] offset1:2
	ds_write2_b64 v157, v[130:131], v[132:133] offset0:4 offset1:6
	s_waitcnt lgkmcnt(0)
	s_waitcnt vmcnt(1) lgkmcnt(2)
	v_mfma_f32_32x32x16_bf16 v[2:17], v[38:41], v[42:45], v[2:17]
	global_load_dwordx4 v[38:41], v[112:113], off
	s_waitcnt vmcnt(1)
	v_mfma_f32_32x32x16_bf16 v[18:33], v[34:37], v[42:45], v[18:33]
	global_load_dwordx4 v[34:37], v[114:115], off
	ds_read_b128 v[42:45], v162
	s_waitcnt vmcnt(1) lgkmcnt(0)
	v_mfma_f32_32x32x16_bf16 v[2:17], v[38:41], v[42:45], v[2:17]
	global_load_dwordx4 v[38:41], v[108:109], off
	s_waitcnt vmcnt(1)
	v_mfma_f32_32x32x16_bf16 v[18:33], v[34:37], v[42:45], v[18:33]
	global_load_dwordx4 v[34:37], v[110:111], off
	ds_read_b128 v[42:45], v162 offset:32
	s_waitcnt lgkmcnt(0)
	ds_write2_b64 v157, v[126:127], v[128:129] offset1:2
	ds_write2_b64 v157, v[122:123], v[124:125] offset0:4 offset1:6
	s_waitcnt lgkmcnt(0)
	s_waitcnt vmcnt(1) lgkmcnt(2)
	v_mfma_f32_32x32x16_bf16 v[2:17], v[38:41], v[42:45], v[2:17]
	global_load_dwordx4 v[38:41], v[104:105], off
	s_waitcnt vmcnt(1)
	v_mfma_f32_32x32x16_bf16 v[18:33], v[34:37], v[42:45], v[18:33]
	global_load_dwordx4 v[34:37], v[106:107], off
	ds_read_b128 v[42:45], v162
	s_waitcnt vmcnt(1) lgkmcnt(0)
	v_mfma_f32_32x32x16_bf16 v[2:17], v[38:41], v[42:45], v[2:17]
	global_load_dwordx4 v[38:41], v[104:105], off offset:32
	s_waitcnt vmcnt(1)
	v_mfma_f32_32x32x16_bf16 v[18:33], v[34:37], v[42:45], v[18:33]
	global_load_dwordx4 v[34:37], v[106:107], off offset:32
	ds_read_b128 v[42:45], v162 offset:32
	s_waitcnt lgkmcnt(0)
	v_lshlrev_b32_e32 v162, 1, v50
	s_waitcnt vmcnt(1) lgkmcnt(0)
	v_mfma_f32_32x32x16_bf16 v[2:17], v[38:41], v[42:45], v[2:17]
	v_div_fixup_f32 v40, v160, v159, 1.0
	v_lshl_add_u64 v[38:39], v[102:103], 0, s[34:35]
	v_lshl_add_u64 v[38:39], v[38:39], 0, v[162:163]
	s_nop 8
	v_pk_mul_f32 v[2:3], v[2:3], v[40:41] op_sel_hi:[1,0]
	s_waitcnt vmcnt(0)
	v_mfma_f32_32x32x16_bf16 v[18:33], v[34:37], v[42:45], v[18:33]
	v_mul_f32_e64 v4, v4, v40
	v_mul_f32_e64 v5, v5, v40
	v_mul_f32_e64 v6, v6, v40
	v_mul_f32_e64 v7, v7, v40
	v_mul_f32_e64 v8, v8, v40
	v_mul_f32_e64 v9, v9, v40
	v_pk_mul_f32 v[10:11], v[10:11], v[40:41] op_sel_hi:[1,0]
	v_pk_mul_f32 v[12:13], v[12:13], v[40:41] op_sel_hi:[1,0]
	v_pk_mul_f32 v[14:15], v[14:15], v[40:41] op_sel_hi:[1,0]
	v_pk_mul_f32 v[16:17], v[16:17], v[40:41] op_sel_hi:[1,0]
	s_nop 1
	v_pk_mul_f32 v[18:19], v[18:19], v[40:41] op_sel_hi:[1,0]
	v_pk_mul_f32 v[20:21], v[20:21], v[40:41] op_sel_hi:[1,0]
	v_pk_mul_f32 v[22:23], v[22:23], v[40:41] op_sel_hi:[1,0]
	v_pk_mul_f32 v[24:25], v[24:25], v[40:41] op_sel_hi:[1,0]
	v_pk_mul_f32 v[26:27], v[26:27], v[40:41] op_sel_hi:[1,0]
	v_pk_mul_f32 v[28:29], v[28:29], v[40:41] op_sel_hi:[1,0]
	v_pk_mul_f32 v[30:31], v[30:31], v[40:41] op_sel_hi:[1,0]
	v_pk_mul_f32 v[32:33], v[32:33], v[40:41] op_sel_hi:[1,0]
	v_cvt_pk_bf16_f32 v2, v2, v3
	v_cvt_pk_bf16_f32 v3, v4, v5
	v_cvt_pk_bf16_f32 v4, v6, v7
	v_cvt_pk_bf16_f32 v5, v8, v9
	v_cvt_pk_bf16_f32 v6, v10, v11
	v_cvt_pk_bf16_f32 v7, v12, v13
	v_cvt_pk_bf16_f32 v8, v14, v15
	v_cvt_pk_bf16_f32 v9, v16, v17
	v_cvt_pk_bf16_f32 v10, v18, v19
	v_cvt_pk_bf16_f32 v11, v20, v21
	v_cvt_pk_bf16_f32 v12, v22, v23
	v_cvt_pk_bf16_f32 v13, v24, v25
	v_cvt_pk_bf16_f32 v14, v26, v27
	v_cvt_pk_bf16_f32 v15, v28, v29
	v_cvt_pk_bf16_f32 v16, v30, v31
	v_cvt_pk_bf16_f32 v17, v32, v33
	global_store_dwordx2 v[38:39], v[2:3], off
	global_store_dwordx2 v[38:39], v[4:5], off offset:16
	global_store_dwordx2 v[38:39], v[6:7], off offset:32
	global_store_dwordx2 v[38:39], v[8:9], off offset:48
	global_store_dwordx2 v[38:39], v[10:11], off offset:64
	global_store_dwordx2 v[38:39], v[12:13], off offset:80
	global_store_dwordx2 v[38:39], v[14:15], off offset:96
	global_store_dwordx2 v[38:39], v[16:17], off offset:112
	s_cbranch_scc0 .LBB0_1419
